# A1 score loop: j=1 sub-tile fragment loads issued up front into free registers instead of four serialized load+vmcnt(0) steps
# speedup vs baseline: 1.0070x; 1.0070x over previous
; #define MFMA32(a, b, c) __builtin_amdgcn_mfma_f32_32x32x16_bf16((a), (b), (c), 0, 0, 0)
; DI void phaseA1(const Params& p, int vblock, int nvblocks, int ubegin, int uend, char* smem) {
;     ...
;     for (int kb = wid; kb < nt; kb += 16) {
;       bf16x8 kf[4][4];
; #pragma unroll
;       for (int j = 0; j < 4; ++j) {
;         const int kt = kb + 4 * j < nt ? kb + 4 * j : kb;
;         const bf16_t* q_ = kib + (size_t)kt * 2048;
;         kf[j][0] = ld16(q_); kf[j][1] = ld16(q_ + 512); kf[j][2] = ld16(q_ + 1024); kf[j][3] = ld16(q_ + 1536);
;       }
; #pragma unroll
;       for (int j = 0; j < 4; ++j) {
;         const int kt = kb + 4 * j;
;         if (kt < nt) {
;           f32x16 s0, s1;
; #pragma unroll
;           for (int e = 0; e < 16; ++e) { s0[e] = 0.f; s1[e] = 0.f; }
; #pragma unroll
;           for (int ks = 0; ks < 4; ++ks) { s0 = MFMA32(af0[ks], kf[j][ks], s0); s1 = MFMA32(af1[ks], kf[j][ks], s1); }
;           float a0 = 0.f, a1 = 0.f, a2 = 0.f, a3 = 0.f;
; #pragma unroll
;           for (int e = 0; e < 8; ++e) {
;             a0 += wr0[e] * fmaxf(s0[e], 0.f); a1 += wr0[8 + e] * fmaxf(s0[8 + e], 0.f);
;             a2 += wr1[e] * fmaxf(s1[e], 0.f); a3 += wr1[8 + e] * fmaxf(s1[8 + e], 0.f);
;           }
;           const int key = kt * 32 + r;
;           sc[(hh * 2 + 0) * 2048 + key] = a0 + 0.0f;
;           sc[(hh * 2 + 1) * 2048 + key] = a1 + 0.0f;
;           sc[(4 + hh * 2 + 0) * 2048 + key] = a2 + 0.0f;
;           sc[(4 + hh * 2 + 1) * 2048 + key] = a3 + 0.0f;
;         }
.LBB0_346:
	global_load_dwordx4 v[2:5], v[112:113], off offset:-3072
	global_load_dwordx4 v[66:69], v[112:113], off offset:-2048
	global_load_dwordx4 v[70:73], v[112:113], off offset:-1024
	global_load_dwordx4 v[154:157], v[112:113], off
	v_add_u32_e32 v152, 4, v151
	v_cmp_lt_i32_e64 s[72:73], s89, v152
	v_cmp_ge_i32_e64 s[74:75], s89, v152
	s_nop 0
	v_cndmask_b32_e64 v172, v152, v151, s[72:73]
	v_ashrrev_i32_e32 v173, 31, v172
	v_lshlrev_b64 v[172:173], 12, v[172:173]
	v_lshl_add_u64 v[172:173], v[114:115], 0, v[172:173]
	global_load_dwordx4 v[190:193], v[172:173], off
	global_load_dwordx4 v[194:197], v[172:173], off offset:1024
	global_load_dwordx4 v[198:201], v[172:173], off offset:2048
	global_load_dwordx4 v[202:205], v[172:173], off offset:3072
	s_waitcnt vmcnt(7)
	v_mfma_f32_32x32x16_bf16 v[18:33], v[34:37], v[2:5], 0
	v_mfma_f32_32x32x16_bf16 v[2:17], v[58:61], v[2:5], 0
	s_waitcnt vmcnt(6)
	v_mfma_f32_32x32x16_bf16 v[18:33], v[38:41], v[66:69], v[18:33]
	v_mfma_f32_32x32x16_bf16 v[2:17], v[42:45], v[66:69], v[2:17]
	v_add_u32_e32 v66, 8, v151
	v_add_u32_e32 v67, 12, v151
	v_cmp_lt_i32_e32 vcc, s89, v66
	v_cmp_lt_i32_e64 s[2:3], s89, v67
	v_cmp_ge_i32_e64 s[70:71], s89, v66
	v_cndmask_b32_e32 v66, v66, v151, vcc
	v_cndmask_b32_e64 v68, v67, v151, s[2:3]
	v_cmp_ge_i32_e32 vcc, s89, v67
	v_ashrrev_i32_e32 v67, 31, v66
	v_ashrrev_i32_e32 v69, 31, v68
	v_lshlrev_b64 v[66:67], 12, v[66:67]
	v_lshlrev_b64 v[68:69], 12, v[68:69]
	v_lshl_add_u64 v[66:67], v[114:115], 0, v[66:67]
	v_lshl_add_u64 v[68:69], v[114:115], 0, v[68:69]
	s_waitcnt vmcnt(5)
	v_mfma_f32_32x32x16_bf16 v[18:33], v[50:53], v[70:73], v[18:33]
	v_mfma_f32_32x32x16_bf16 v[2:17], v[46:49], v[70:73], v[2:17]
	global_load_dwordx4 v[94:97], v[66:67], off
	global_load_dwordx4 v[90:93], v[66:67], off offset:1024
	global_load_dwordx4 v[86:89], v[66:67], off offset:2048
	global_load_dwordx4 v[82:85], v[66:67], off offset:3072
	global_load_dwordx4 v[78:81], v[68:69], off
	global_load_dwordx4 v[74:77], v[68:69], off offset:1024
	global_load_dwordx4 v[70:73], v[68:69], off offset:2048
	s_nop 0
	global_load_dwordx4 v[66:69], v[68:69], off offset:3072
	s_waitcnt vmcnt(12)
	v_mfma_f32_32x32x16_bf16 v[18:33], v[54:57], v[154:157], v[18:33]
	v_mfma_f32_32x32x16_bf16 v[2:17], v[62:65], v[154:157], v[2:17]
	s_nop 10
	v_max_f32_e32 v18, v18, v18
	v_max_f32_e32 v19, v19, v19
	v_max_f32_e32 v18, 0, v18
	v_max_f32_e32 v26, v26, v26
	v_max_f32_e32 v20, v20, v20
	v_max_f32_e32 v19, 0, v19
	v_fma_f32 v18, v111, v18, 0
	v_max_f32_e32 v27, v27, v27
	v_max_f32_e32 v21, v21, v21
	v_max_f32_e32 v26, 0, v26
	v_max_f32_e32 v20, 0, v20
	v_fmac_f32_e32 v18, v119, v19
	v_max_f32_e32 v2, v2, v2
	v_max_f32_e32 v28, v28, v28
	v_max_f32_e32 v22, v22, v22
	v_max_f32_e32 v27, 0, v27
	v_max_f32_e32 v21, 0, v21
	v_fma_f32 v26, v126, v26, 0
	v_fmac_f32_e32 v18, v120, v20
	v_max_f32_e32 v3, v3, v3
	v_max_f32_e32 v29, v29, v29
	v_max_f32_e32 v23, v23, v23
	v_max_f32_e32 v2, 0, v2
	v_max_f32_e32 v28, 0, v28
	v_max_f32_e32 v22, 0, v22
	v_fmac_f32_e32 v26, v127, v27
	v_fmac_f32_e32 v18, v121, v21
	v_max_f32_e32 v10, v10, v10
	v_max_f32_e32 v4, v4, v4
	v_max_f32_e32 v30, v30, v30
	v_max_f32_e32 v24, v24, v24
	v_max_f32_e32 v3, 0, v3
	v_max_f32_e32 v29, 0, v29
	v_max_f32_e32 v23, 0, v23
	v_fma_f32 v2, v134, v2, 0
	v_fmac_f32_e32 v26, v128, v28
	v_fmac_f32_e32 v18, v122, v22
	v_max_f32_e32 v11, v11, v11
	v_max_f32_e32 v5, v5, v5
	v_max_f32_e32 v31, v31, v31
	v_max_f32_e32 v10, 0, v10
	v_max_f32_e32 v4, 0, v4
	v_max_f32_e32 v30, 0, v30
	v_max_f32_e32 v24, 0, v24
	v_fmac_f32_e32 v2, v135, v3
	v_fmac_f32_e32 v26, v129, v29
	v_fmac_f32_e32 v18, v123, v23
	v_max_f32_e32 v3, v25, v25
	v_max_f32_e32 v12, v12, v12
	v_max_f32_e32 v6, v6, v6
	v_max_f32_e32 v32, v32, v32
	v_max_f32_e32 v11, 0, v11
	v_max_f32_e32 v5, 0, v5
	v_max_f32_e32 v31, 0, v31
	v_fma_f32 v10, v142, v10, 0
	v_fmac_f32_e32 v2, v136, v4
	v_fmac_f32_e32 v26, v130, v30
	v_fmac_f32_e32 v18, v124, v24
	v_max_f32_e32 v3, 0, v3
	v_max_f32_e32 v13, v13, v13
	v_max_f32_e32 v7, v7, v7
	v_max_f32_e32 v12, 0, v12
	v_max_f32_e32 v6, 0, v6
	v_max_f32_e32 v32, 0, v32
	v_fmac_f32_e32 v10, v143, v11
	v_fmac_f32_e32 v2, v137, v5
	v_fmac_f32_e32 v26, v131, v31
	v_fmac_f32_e32 v18, v125, v3
	v_max_f32_e32 v3, v33, v33
	v_max_f32_e32 v14, v14, v14
	v_max_f32_e32 v8, v8, v8
	v_max_f32_e32 v13, 0, v13
	v_max_f32_e32 v7, 0, v7
	v_fmac_f32_e32 v10, v144, v12
	v_fmac_f32_e32 v2, v138, v6
	v_fmac_f32_e32 v26, v132, v32
	v_max_f32_e32 v3, 0, v3
	v_max_f32_e32 v15, v15, v15
	v_max_f32_e32 v14, 0, v14
	v_max_f32_e32 v8, 0, v8
	v_fmac_f32_e32 v10, v145, v13
	v_fmac_f32_e32 v2, v139, v7
	v_fmac_f32_e32 v26, v133, v3
	v_max_f32_e32 v3, v9, v9
	v_max_f32_e32 v16, v16, v16
	v_max_f32_e32 v15, 0, v15
	v_fmac_f32_e32 v10, v146, v14
	v_fmac_f32_e32 v2, v140, v8
	v_max_f32_e32 v3, 0, v3
	v_max_f32_e32 v16, 0, v16
	v_fmac_f32_e32 v10, v147, v15
	v_fmac_f32_e32 v2, v141, v3
	v_max_f32_e32 v3, v17, v17
	v_fmac_f32_e32 v10, v148, v16
	v_max_f32_e32 v3, 0, v3
	v_fmac_f32_e32 v10, v149, v3
	v_add_f32_e32 v3, 0, v18
	v_add_f32_e32 v4, 0, v26
	ds_write2st64_b32 v150, v3, v4 offset1:32
	v_add_f32_e32 v2, 0, v2
	v_add_f32_e32 v3, 0, v10
	ds_write2st64_b32 v150, v2, v3 offset0:128 offset1:160
	s_and_saveexec_b64 s[2:3], s[74:75]
	s_cbranch_execz .LBB0_349
; #define MFMA32(a, b, c) __builtin_amdgcn_mfma_f32_32x32x16_bf16((a), (b), (c), 0, 0, 0)
; DI void phaseA1(const Params& p, int vblock, int nvblocks, int ubegin, int uend, char* smem) {
;     ...
; #pragma unroll
;       for (int j = 0; j < 4; ++j) {
;         const int kt = kb + 4 * j;
;         if (kt < nt) {
;           f32x16 s0, s1;
; #pragma unroll
;           for (int e = 0; e < 16; ++e) { s0[e] = 0.f; s1[e] = 0.f; }
; #pragma unroll
;           for (int ks = 0; ks < 4; ++ks) { s0 = MFMA32(af0[ks], kf[j][ks], s0); s1 = MFMA32(af1[ks], kf[j][ks], s1); }
;           float a0 = 0.f, a1 = 0.f, a2 = 0.f, a3 = 0.f;
; #pragma unroll
;           for (int e = 0; e < 8; ++e) {
;             a0 += wr0[e] * fmaxf(s0[e], 0.f); a1 += wr0[8 + e] * fmaxf(s0[8 + e], 0.f);
;             a2 += wr1[e] * fmaxf(s1[e], 0.f); a3 += wr1[8 + e] * fmaxf(s1[8 + e], 0.f);
;           }
;           const int key = kt * 32 + r;
;           sc[(hh * 2 + 0) * 2048 + key] = a0 + 0.0f;
;           sc[(hh * 2 + 1) * 2048 + key] = a1 + 0.0f;
;           sc[(4 + hh * 2 + 0) * 2048 + key] = a2 + 0.0f;
;           sc[(4 + hh * 2 + 1) * 2048 + key] = a3 + 0.0f;
;         }
	s_waitcnt vmcnt(8)
	v_mfma_f32_32x32x16_bf16 v[18:33], v[34:37], v[190:193], 0
	v_mfma_f32_32x32x16_bf16 v[2:17], v[58:61], v[190:193], 0
	v_mfma_f32_32x32x16_bf16 v[18:33], v[38:41], v[194:197], v[18:33]
	v_mfma_f32_32x32x16_bf16 v[2:17], v[42:45], v[194:197], v[2:17]
	v_mfma_f32_32x32x16_bf16 v[18:33], v[50:53], v[198:201], v[18:33]
	v_mfma_f32_32x32x16_bf16 v[2:17], v[46:49], v[198:201], v[2:17]
	v_mfma_f32_32x32x16_bf16 v[18:33], v[54:57], v[202:205], v[18:33]
	s_nop 11
	v_max_f32_e32 v18, v18, v18
	v_mfma_f32_32x32x16_bf16 v[2:17], v[62:65], v[202:205], v[2:17]
	v_max_f32_e32 v26, v26, v26
	v_max_f32_e32 v19, v19, v19
	v_max_f32_e32 v27, v27, v27
	v_max_f32_e32 v18, 0, v18
	v_max_f32_e32 v26, 0, v26
	v_max_f32_e32 v20, v20, v20
	v_max_f32_e32 v28, v28, v28
	s_nop 4
	v_max_f32_e32 v2, v2, v2
	v_max_f32_e32 v10, v10, v10
	v_max_f32_e32 v3, v3, v3
	v_max_f32_e32 v11, v11, v11
	v_max_f32_e32 v2, 0, v2
	v_max_f32_e32 v10, 0, v10
	v_max_f32_e32 v19, 0, v19
	v_max_f32_e32 v27, 0, v27
	v_fma_f32 v18, v111, v18, 0
	v_fma_f32 v26, v126, v26, 0
	v_max_f32_e32 v4, v4, v4
	v_max_f32_e32 v12, v12, v12
	v_max_f32_e32 v21, v21, v21
	v_max_f32_e32 v29, v29, v29
	v_max_f32_e32 v3, 0, v3
	v_max_f32_e32 v11, 0, v11
	v_max_f32_e32 v20, 0, v20
	v_max_f32_e32 v28, 0, v28
	v_fma_f32 v2, v134, v2, 0
	v_fma_f32 v10, v142, v10, 0
	v_fmac_f32_e32 v18, v119, v19
	v_fmac_f32_e32 v26, v127, v27
	v_max_f32_e32 v5, v5, v5
	v_max_f32_e32 v13, v13, v13
	v_max_f32_e32 v22, v22, v22
	v_max_f32_e32 v30, v30, v30
	v_max_f32_e32 v4, 0, v4
	v_max_f32_e32 v12, 0, v12
	v_max_f32_e32 v21, 0, v21
	v_max_f32_e32 v29, 0, v29
	v_fmac_f32_e32 v2, v135, v3
	v_fmac_f32_e32 v10, v143, v11
	v_fmac_f32_e32 v18, v120, v20
	v_fmac_f32_e32 v26, v128, v28
	v_max_f32_e32 v6, v6, v6
	v_max_f32_e32 v14, v14, v14
	v_max_f32_e32 v23, v23, v23
	v_max_f32_e32 v31, v31, v31
	v_max_f32_e32 v5, 0, v5
	v_max_f32_e32 v13, 0, v13
	v_max_f32_e32 v22, 0, v22
	v_max_f32_e32 v30, 0, v30
	v_fmac_f32_e32 v2, v136, v4
	v_fmac_f32_e32 v10, v144, v12
	v_fmac_f32_e32 v18, v121, v21
	v_fmac_f32_e32 v26, v129, v29
	v_max_f32_e32 v7, v7, v7
	v_max_f32_e32 v15, v15, v15
	v_max_f32_e32 v24, v24, v24
	v_max_f32_e32 v32, v32, v32
	v_max_f32_e32 v6, 0, v6
	v_max_f32_e32 v14, 0, v14
	v_max_f32_e32 v23, 0, v23
	v_max_f32_e32 v31, 0, v31
	v_fmac_f32_e32 v2, v137, v5
	v_fmac_f32_e32 v10, v145, v13
	v_fmac_f32_e32 v18, v122, v22
	v_fmac_f32_e32 v26, v130, v30
	v_max_f32_e32 v8, v8, v8
	v_max_f32_e32 v16, v16, v16
	v_max_f32_e32 v25, v25, v25
	v_max_f32_e32 v33, v33, v33
	v_max_f32_e32 v7, 0, v7
	v_max_f32_e32 v15, 0, v15
	v_max_f32_e32 v24, 0, v24
	v_max_f32_e32 v32, 0, v32
	v_fmac_f32_e32 v2, v138, v6
	v_fmac_f32_e32 v10, v146, v14
	v_fmac_f32_e32 v18, v123, v23
	v_fmac_f32_e32 v26, v131, v31
	v_max_f32_e32 v9, v9, v9
	v_max_f32_e32 v17, v17, v17
	v_max_f32_e32 v8, 0, v8
	v_max_f32_e32 v16, 0, v16
	v_max_f32_e32 v25, 0, v25
	v_max_f32_e32 v33, 0, v33
	v_fmac_f32_e32 v2, v139, v7
	v_fmac_f32_e32 v10, v147, v15
	v_fmac_f32_e32 v18, v124, v24
	v_fmac_f32_e32 v26, v132, v32
	v_max_f32_e32 v9, 0, v9
	v_max_f32_e32 v17, 0, v17
	v_fmac_f32_e32 v2, v140, v8
	v_fmac_f32_e32 v10, v148, v16
	v_fmac_f32_e32 v18, v125, v25
	v_fmac_f32_e32 v26, v133, v33
	v_fmac_f32_e32 v2, v141, v9
	v_fmac_f32_e32 v10, v149, v17
	v_add_f32_e32 v3, 0, v18
	v_add_f32_e32 v4, 0, v26
	v_add_f32_e32 v2, 0, v2
	v_add_f32_e32 v5, 0, v10
	ds_write2st64_b32 v150, v3, v4 offset0:2 offset1:34
	ds_write2st64_b32 v150, v2, v5 offset0:130 offset1:162
	s_or_b64 exec, exec, s[2:3]
	s_and_saveexec_b64 s[2:3], s[70:71]
	s_cbranch_execnz .LBB0_350
